# retd items redistributed away from WGs with extra attention/gmlp items (stride 236 in layers 0-2)
# speedup vs baseline: 1.0043x; 1.0043x over previous
.LBB0_258:
	v_readlane_b32 s11, v254, 30
	s_mul_hi_u32 s10, s2, s11
	v_readlane_b32 s15, v254, 29
	s_mul_i32 s10, s10, s15
	s_sub_i32 s2, s2, s10
	s_add_i32 s3, s3, s96
	s_sub_i32 s10, s2, s15
	s_cmp_ge_u32 s2, s15
	s_cselect_b32 s2, s10, s2
	s_sub_i32 s10, s2, s15
	s_cmp_ge_u32 s2, s15
	s_cselect_b32 s2, s10, s2
	s_sub_i32 s2, s3, s2
	s_ashr_i32 s3, s2, 31
	s_abs_i32 s2, s2
	s_mul_hi_u32 s10, s2, s11
	s_mul_i32 s10, s10, s15
	s_sub_i32 s2, s2, s10
	s_sub_i32 s10, s2, s15
	s_cmp_ge_u32 s2, s15
	s_cselect_b32 s2, s10, s2
	s_sub_i32 s10, s2, s15
	s_cmp_ge_u32 s2, s15
	s_cselect_b32 s2, s10, s2
	s_xor_b32 s2, s2, s3
	s_sub_i32 s10, s2, s3
	v_readlane_b32 s2, v255, 36
	v_readlane_b32 s3, v255, 37
	s_lshl_b64 s[2:3], s[2:3], 2
	v_readlane_b32 s20, v255, 18
	v_readlane_b32 s21, v255, 19
	s_add_u32 s2, s20, s2
	s_addc_u32 s3, s21, s3
	s_add_i32 s10, s10, s57
	s_ashr_i32 s22, s10, 31
	s_abs_i32 s10, s10
	s_mul_hi_u32 s11, s10, s11
	s_mul_i32 s11, s11, s15
	s_sub_i32 s10, s10, s11
	s_sub_i32 s11, s10, s15
	s_cmp_ge_u32 s10, s15
	s_cselect_b32 s10, s11, s10
	s_sub_i32 s11, s10, s15
	s_cmp_ge_u32 s10, s15
	s_cselect_b32 s10, s11, s10
	s_xor_b32 s23, s10, s22
	s_sub_i32 s15, s23, s22
	s_sub_i32 s100, s15, s57
	s_and_b32 s100, s100, 0xff
	s_cmp_eq_u32 s100, 0
	s_cselect_b32 s100, s96, s100
	s_cmp_lt_i32 s15, s100
	s_cselect_b64 s[10:11], -1, 0
	s_lshl_b32 s16, s15, 5
	s_and_b32 s16, s16, 0xffffff80
	v_add_u32_e32 v0, s16, v139
	v_mov_b64_e32 v[2:3], s[72:73]
	s_lshl_b32 s16, s15, 7
	v_mad_i64_i32 v[2:3], s[20:21], v0, s64, v[2:3]
	s_and_b32 s16, s16, 0x180
	v_lshl_add_u64 v[2:3], v[2:3], 0, s[16:17]
	v_lshlrev_b32_e32 v0, 1, v142
	s_waitcnt vmcnt(0)
	v_lshl_add_u64 v[30:31], v[2:3], 0, v[0:1]
	v_sub_u32_e32 v2, 0x7f, v139
	v_readlane_b32 s20, v255, 24
	v_cvt_f32_i32_e32 v36, v2
	v_lshlrev_b32_e32 v2, 2, v145
	v_mov_b32_e32 v3, v1
	v_readlane_b32 s21, v255, 25
	v_cvt_f32_i32_e32 v37, v139
	s_lshl_b32 s16, s23, 1
	v_lshl_add_u64 v[32:33], s[20:21], 0, v[2:3]
	s_lshl_b32 s20, s22, 1
	s_sub_i32 s20, s16, s20
	s_add_i32 s16, s100, s23
	v_mul_u32_u24_e32 v2, 0x90, v154
	s_sub_i32 s16, s16, s22
	v_lshlrev_b32_e32 v38, 8, v147
	v_add3_u32 v39, v2, v155, 0
	s_lshl_b32 s21, s16, 5
	s_lshl_b32 s28, s16, 6
	s_mov_b32 s29, 0
	s_branch .LBB0_260

.LBB0_262:
	v_add_u32_e32 v52, s41, v39
	v_add_u32_e32 v53, s40, v39
	ds_read_b64_tr_b16 v[18:19], v52 offset:36864
	ds_read_b64_tr_b16 v[20:21], v52 offset:39168
	ds_read_b64_tr_b16 v[24:25], v53 offset:2304
	ds_read_b64_tr_b16 v[22:23], v53
	ds_read_b64_tr_b16 v[26:27], v53 offset:32
	ds_read_b64_tr_b16 v[28:29], v53 offset:2336
	ds_read_b64_tr_b16 v[40:41], v53 offset:64
	ds_read_b64_tr_b16 v[42:43], v53 offset:2368
	ds_read_b64_tr_b16 v[44:45], v53 offset:96
	ds_read_b64_tr_b16 v[46:47], v53 offset:2400
	s_waitcnt lgkmcnt(6)
	v_mfma_f32_16x16x32_bf16 v[22:25], v[18:21], v[22:25], 0
	s_ashr_i32 s23, s22, 31
	s_lshl_b32 s16, s100, 1
	s_lshl_b64 s[46:47], s[22:23], 14
	s_waitcnt lgkmcnt(4)
	v_mfma_f32_16x16x32_bf16 v[26:29], v[18:21], v[26:29], 0
	s_add_i32 s22, s22, s16
	s_lshl_b32 s16, s100, 5
	s_add_i32 s43, s43, s16
	s_waitcnt lgkmcnt(2)
	v_mfma_f32_16x16x32_bf16 v[40:43], v[18:21], v[40:43], 0
	s_lshl_b32 s16, s100, 6
	s_add_i32 s42, s42, s16
	s_andn2_b64 vcc, exec, s[26:27]
	s_waitcnt lgkmcnt(0)
	v_mfma_f32_16x16x32_bf16 v[18:21], v[18:21], v[44:47], 0
	ds_read_b64_tr_b16 v[44:45], v52 offset:41472
	ds_read_b64_tr_b16 v[46:47], v52 offset:43776
	ds_read_b64_tr_b16 v[48:49], v53 offset:4608
	ds_read_b64_tr_b16 v[50:51], v53 offset:6912
	s_waitcnt lgkmcnt(0)
	v_mfma_f32_16x16x32_bf16 v[22:25], v[44:47], v[48:51], v[22:25]
	ds_read_b64_tr_b16 v[48:49], v53 offset:4640
	ds_read_b64_tr_b16 v[50:51], v53 offset:6944
	s_waitcnt lgkmcnt(0)
	v_mfma_f32_16x16x32_bf16 v[26:29], v[44:47], v[48:51], v[26:29]
	ds_read_b64_tr_b16 v[48:49], v53 offset:4672
	ds_read_b64_tr_b16 v[50:51], v53 offset:6976
	s_waitcnt lgkmcnt(0)
	v_mfma_f32_16x16x32_bf16 v[40:43], v[44:47], v[48:51], v[40:43]
	ds_read_b64_tr_b16 v[48:49], v53 offset:4704
	ds_read_b64_tr_b16 v[50:51], v53 offset:7008
	s_waitcnt lgkmcnt(0)
	v_mfma_f32_16x16x32_bf16 v[18:21], v[44:47], v[48:51], v[18:21]
	ds_read_b64_tr_b16 v[44:45], v52 offset:46080
	ds_read_b64_tr_b16 v[46:47], v52 offset:48384
	ds_read_b64_tr_b16 v[48:49], v53 offset:9216
	ds_read_b64_tr_b16 v[50:51], v53 offset:11520
	s_waitcnt lgkmcnt(0)
	v_mfma_f32_16x16x32_bf16 v[22:25], v[44:47], v[48:51], v[22:25]
	ds_read_b64_tr_b16 v[48:49], v53 offset:9248
	ds_read_b64_tr_b16 v[50:51], v53 offset:11552
	s_waitcnt lgkmcnt(0)
	v_mfma_f32_16x16x32_bf16 v[26:29], v[44:47], v[48:51], v[26:29]
	ds_read_b64_tr_b16 v[48:49], v53 offset:9280
	ds_read_b64_tr_b16 v[50:51], v53 offset:11584
	s_waitcnt lgkmcnt(0)
	v_mfma_f32_16x16x32_bf16 v[40:43], v[44:47], v[48:51], v[40:43]
	ds_read_b64_tr_b16 v[48:49], v53 offset:9312
	ds_read_b64_tr_b16 v[50:51], v53 offset:11616
	s_waitcnt lgkmcnt(0)
	v_mfma_f32_16x16x32_bf16 v[18:21], v[44:47], v[48:51], v[18:21]
	ds_read_b64_tr_b16 v[44:45], v52 offset:50688
	ds_read_b64_tr_b16 v[46:47], v52 offset:52992
	ds_read_b64_tr_b16 v[48:49], v53 offset:13824
	ds_read_b64_tr_b16 v[50:51], v53 offset:16128
	s_waitcnt lgkmcnt(0)
	v_mfma_f32_16x16x32_bf16 v[22:25], v[44:47], v[48:51], v[22:25]
	ds_read_b64_tr_b16 v[48:49], v53 offset:13856
	ds_read_b64_tr_b16 v[50:51], v53 offset:16160
	s_waitcnt lgkmcnt(0)
	v_mfma_f32_16x16x32_bf16 v[26:29], v[44:47], v[48:51], v[26:29]
	ds_read_b64_tr_b16 v[48:49], v53 offset:13888
	ds_read_b64_tr_b16 v[50:51], v53 offset:16192
	s_waitcnt lgkmcnt(0)
	v_mfma_f32_16x16x32_bf16 v[40:43], v[44:47], v[48:51], v[40:43]
	ds_read_b64_tr_b16 v[48:49], v53 offset:13920
	ds_read_b64_tr_b16 v[50:51], v53 offset:16224
	s_waitcnt lgkmcnt(0)
	v_mfma_f32_16x16x32_bf16 v[18:21], v[44:47], v[48:51], v[18:21]
	v_lshl_add_u64 v[44:45], v[34:35], 0, s[46:47]
	global_store_dword v[44:45], v22, off
	global_store_dword v[44:45], v23, off offset:256
	global_store_dword v[44:45], v24, off offset:512
	global_store_dword v[44:45], v25, off offset:768
	global_store_dword v[44:45], v26, off offset:64
	global_store_dword v[44:45], v27, off offset:320
	global_store_dword v[44:45], v28, off offset:576
	global_store_dword v[44:45], v29, off offset:832
	global_store_dword v[44:45], v40, off offset:128
	global_store_dword v[44:45], v41, off offset:384
	global_store_dword v[44:45], v42, off offset:640
	global_store_dword v[44:45], v43, off offset:896
	global_store_dword v[44:45], v18, off offset:192
	global_store_dword v[44:45], v19, off offset:448
	global_store_dword v[44:45], v20, off offset:704
	global_store_dword v[44:45], v21, off offset:960
	s_barrier
	s_cbranch_vccz .LBB0_259

.Lmy_rd_j:
	v_mov_b32_e32 v19, v201
	v_mov_b32_e32 v18, v200
	v_and_b32_e32 v20, 0xffff0000, v6
	v_lshlrev_b32_e32 v23, 16, v2
	v_and_b32_e32 v27, 0xffff0000, v2
	v_lshlrev_b32_e32 v21, 16, v7
	v_and_b32_e32 v24, 0xffff0000, v7
	v_lshlrev_b32_e32 v41, 16, v3
	v_and_b32_e32 v42, 0xffff0000, v3
	v_lshlrev_b32_e32 v28, 16, v8
	v_and_b32_e32 v29, 0xffff0000, v8
	v_lshlrev_b32_e32 v46, 16, v4
	v_and_b32_e32 v47, 0xffff0000, v4
	v_lshlrev_b32_e32 v44, 16, v9
	v_and_b32_e32 v45, 0xffff0000, v9
	v_lshlrev_b32_e32 v48, 16, v5
	v_and_b32_e32 v49, 0xffff0000, v5
	s_add_i32 s44, s44, s100
	s_cmpk_gt_i32 s44, 0x40f
	s_cselect_b64 s[26:27], -1, 0
	s_and_b64 vcc, exec, s[26:27]
	s_nop 0
	v_mul_f32_e32 v19, v19, v36
	v_exp_f32_e32 v25, v19
	s_nop 0
	v_mul_f32_e32 v18, v18, v37
	v_exp_f32_e32 v43, v18
	v_lshlrev_b32_e32 v19, 16, v6
	v_mul_f32_e32 v18, v25, v19
	v_mul_f32_e32 v22, v25, v20
	v_cvt_pk_bf16_f32 v18, v18, v22
	v_mul_f32_e32 v22, v25, v23
	v_mul_f32_e32 v26, v25, v27
	v_mul_f32_e32 v19, v43, v19
	v_mul_f32_e32 v20, v43, v20
	v_cvt_pk_bf16_f32 v22, v22, v26
	v_cvt_pk_bf16_f32 v26, v19, v20
	v_mul_f32_e32 v19, v43, v23
	v_mul_f32_e32 v20, v43, v27
	v_cvt_pk_bf16_f32 v40, v19, v20
	v_mul_f32_e32 v19, v25, v21
	v_mul_f32_e32 v20, v25, v24
	v_cvt_pk_bf16_f32 v19, v19, v20
	v_mul_f32_e32 v20, v25, v41
	v_mul_f32_e32 v23, v25, v42
	v_cvt_pk_bf16_f32 v23, v20, v23
	v_mul_f32_e32 v20, v43, v21
	v_mul_f32_e32 v21, v43, v24
	v_cvt_pk_bf16_f32 v27, v20, v21
	v_mul_f32_e32 v20, v43, v41
	v_mul_f32_e32 v21, v43, v42
	v_cvt_pk_bf16_f32 v41, v20, v21
	v_mul_f32_e32 v20, v25, v28
	v_mul_f32_e32 v21, v25, v29
	v_cvt_pk_bf16_f32 v20, v20, v21
	v_mul_f32_e32 v21, v25, v46
	v_mul_f32_e32 v24, v25, v47
	v_cvt_pk_bf16_f32 v24, v21, v24
	v_mul_f32_e32 v21, v43, v28
	v_mul_f32_e32 v28, v43, v29
	v_cvt_pk_bf16_f32 v28, v21, v28
	v_mul_f32_e32 v21, v43, v46
	v_mul_f32_e32 v29, v43, v47
	v_cvt_pk_bf16_f32 v42, v21, v29
	v_mul_f32_e32 v21, v25, v44
	v_mul_f32_e32 v29, v25, v45
	v_cvt_pk_bf16_f32 v21, v21, v29
	v_mul_f32_e32 v29, v25, v48
	v_mul_f32_e32 v25, v25, v49
	v_cvt_pk_bf16_f32 v25, v29, v25
	v_mul_f32_e32 v29, v43, v44
	v_mul_f32_e32 v44, v43, v45
	v_cvt_pk_bf16_f32 v29, v29, v44
	v_mul_f32_e32 v44, v43, v48
	v_mul_f32_e32 v43, v43, v49
	v_cvt_pk_bf16_f32 v43, v44, v43
	v_add_u32_e32 v44, v143, v141
	ds_write_b128 v44, v[18:21]
	ds_write_b128 v44, v[22:25] offset:16
	ds_write_b128 v44, v[26:29] offset:18432
	ds_write_b128 v44, v[40:43] offset:18448
	ds_write_b128 v44, v[14:17] offset:36864
	ds_write_b128 v44, v[10:13] offset:36880
	s_waitcnt lgkmcnt(0)
	s_barrier
	s_cbranch_vccnz .LBB0_262
	s_and_b32 s16, s43, 0xffffff80
	v_add_u32_e32 v4, s16, v139
	v_mov_b64_e32 v[2:3], s[72:73]
	s_and_b32 s16, s42, 0xc0
	v_mad_i64_i32 v[2:3], s[46:47], v4, s64, v[2:3]
	s_lshl_b32 s16, s16, 1
	v_lshl_add_u64 v[2:3], v[2:3], 0, s[16:17]
	v_lshl_add_u64 v[14:15], v[2:3], 0, v[0:1]
	global_load_dwordx4 v[2:5], v[14:15], off offset:528
	global_load_dwordx4 v[6:9], v[14:15], off offset:512
	global_load_dwordx4 v[10:13], v[14:15], off offset:1040
	s_nop 0
	global_load_dwordx4 v[14:17], v[14:15], off offset:1024
	s_and_b32 s99, s44, 3
	s_lshl_b32 s99, s99, 2
	v_mov_b32_e32 v200, s99
	global_load_dword v201, v200, s[2:3]
	global_load_dword v200, v200, s[2:3] offset:16
	s_branch .LBB0_262
